# v043 + grid barrier arrival generation is the site ordinal: the two unsigned divisions per barrier replaced by a constant and one multiply
# speedup vs baseline: 1.0016x; 1.0002x over previous
; __device__ __forceinline__ unsigned xb_ld(unsigned* p)              { return __hip_atomic_load(p, __ATOMIC_RELAXED, __HIP_MEMORY_SCOPE_AGENT); }
; __device__ __forceinline__ unsigned xb_add(unsigned* p, unsigned v) { return __hip_atomic_fetch_add(p, v, __ATOMIC_RELAXED, __HIP_MEMORY_SCOPE_AGENT); }
; #define XB_SPIN(cond, bar) do { unsigned _sp = 0; while (cond) { __builtin_amdgcn_s_sleep(1); \
;     if ((++_sp & 255u) == 0u) { if (xb_ld(&(bar)[XB_TMO])) break; if (_sp > XB_SPIN_CAP) { atomicAdd(&(bar)[XB_TMO], 1u); break; } } } } while (0)
; __device__ __forceinline__ void xcd_barrier(const XcdBarrier& b) {
;     ...
;         const unsigned old = xb_add(&bar[XB_XSUB(b.x)], 1u);
;         const unsigned gen = old / nloc;
;         if (old + 1u == (gen + 1u) * nloc) {
;     ...
;         } else {
;             XB_SPIN(xb_ld(&bar[XB_XGEN(b.x)]) == gen, bar);
.LBB0_65:
	s_or_b64 exec, exec, s[10:11]
	s_waitcnt vmcnt(0)
	v_readfirstlane_b32 s8, v4
	v_mul_u32_u24_e32 v3, 1, v3
	s_nop 1
	v_add_u32_e32 v6, s8, v2
	v_mov_b32_e32 v2, 0
	v_add_u32_e32 v4, 1, v6
	v_cmp_ne_u32_e32 vcc, v4, v3
	s_and_saveexec_b64 s[8:9], vcc
	s_xor_b64 s[8:9], exec, s[8:9]
	s_cbranch_execz .LBB0_79
	s_waitcnt lgkmcnt(0)
	v_mov_b32_e32 v1, 0x2000
	global_load_dword v1, v1, s[6:7] offset:1024 sc1
	s_add_u32 s14, s6, 0x2400
	s_addc_u32 s15, s7, 0
	s_waitcnt vmcnt(0)
	v_cmp_eq_u32_e32 vcc, v1, v2
	s_and_saveexec_b64 s[10:11], vcc
	s_cbranch_execz .LBB0_78
	s_add_u32 s12, s26, 0x700200
	s_addc_u32 s13, s27, 0
	s_mov_b32 s23, 1
	s_mov_b64 s[16:17], 0
	v_mov_b32_e32 v1, 0
	s_branch .LBB0_69

; __device__ __forceinline__ unsigned xb_ld(unsigned* p)              { return __hip_atomic_load(p, __ATOMIC_RELAXED, __HIP_MEMORY_SCOPE_AGENT); }
; __device__ __forceinline__ unsigned xb_add(unsigned* p, unsigned v) { return __hip_atomic_fetch_add(p, v, __ATOMIC_RELAXED, __HIP_MEMORY_SCOPE_AGENT); }
; #define XB_SPIN(cond, bar) do { unsigned _sp = 0; while (cond) { __builtin_amdgcn_s_sleep(1); \
;     if ((++_sp & 255u) == 0u) { if (xb_ld(&(bar)[XB_TMO])) break; if (_sp > XB_SPIN_CAP) { atomicAdd(&(bar)[XB_TMO], 1u); break; } } } } while (0)
; __device__ __forceinline__ void xcd_barrier(const XcdBarrier& b) {
;     ...
;             __builtin_amdgcn_fence(__ATOMIC_RELEASE, "agent");
;             asm volatile("s_waitcnt vmcnt(0)" ::: "memory");
;             const unsigned og = xb_add(&bar[XB_TOP], 1u);
;             const unsigned tg = og / nx;
;             if (og + 1u == (tg + 1u) * nx) xb_add(&bar[XB_TOPGEN], 1u);
;             else XB_SPIN(xb_ld(&bar[XB_TOPGEN]) == tg, bar);
.LBB0_82:
	s_or_b64 exec, exec, s[10:11]
	s_waitcnt vmcnt(0)
	v_readfirstlane_b32 s8, v3
	v_mul_u32_u24_e32 v1, 1, v1
	s_add_u32 s10, s26, 0x703500
	s_addc_u32 s11, s27, 0
	s_mov_b64 s[12:13], -1
	s_nop 1
	v_add_u32_e32 v2, s8, v2
	v_mov_b32_e32 v4, 0
	v_add_u32_e32 v5, 1, v2
	v_cmp_ne_u32_e32 vcc, v5, v1
	v_mov_b64_e32 v[2:3], s[10:11]
	s_and_saveexec_b64 s[8:9], vcc
	s_cbranch_execz .LBB0_94
	v_mov_b32_e32 v1, 0
	global_load_dword v2, v1, s[10:11] sc1
	s_mov_b64 s[16:17], 0
	s_waitcnt vmcnt(0)
	v_cmp_eq_u32_e32 vcc, v2, v4
	s_and_saveexec_b64 s[14:15], vcc
	s_cbranch_execz .LBB0_93
	s_add_u32 s12, s26, 0x700200
	s_addc_u32 s13, s27, 0
	s_mov_b32 s23, 1
	s_branch .LBB0_86

; __device__ __forceinline__ unsigned xb_ld(unsigned* p)              { return __hip_atomic_load(p, __ATOMIC_RELAXED, __HIP_MEMORY_SCOPE_AGENT); }
; __device__ __forceinline__ unsigned xb_add(unsigned* p, unsigned v) { return __hip_atomic_fetch_add(p, v, __ATOMIC_RELAXED, __HIP_MEMORY_SCOPE_AGENT); }
; #define XB_SPIN(cond, bar) do { unsigned _sp = 0; while (cond) { __builtin_amdgcn_s_sleep(1); \
;     if ((++_sp & 255u) == 0u) { if (xb_ld(&(bar)[XB_TMO])) break; if (_sp > XB_SPIN_CAP) { atomicAdd(&(bar)[XB_TMO], 1u); break; } } } } while (0)
; __device__ __forceinline__ void xcd_barrier(const XcdBarrier& b) {
;     ...
;         const unsigned old = xb_add(&bar[XB_XSUB(b.x)], 1u);
;         const unsigned gen = old / nloc;
;         if (old + 1u == (gen + 1u) * nloc) {
;     ...
;         } else {
;             XB_SPIN(xb_ld(&bar[XB_XGEN(b.x)]) == gen, bar);
.LBB0_128:
	s_or_b64 exec, exec, s[10:11]
	s_waitcnt vmcnt(0)
	v_readfirstlane_b32 s8, v5
	v_mul_u32_u24_e32 v4, 2, v4
	s_nop 1
	v_add_u32_e32 v7, s8, v3
	v_mov_b32_e32 v3, 1
	v_add_u32_e32 v5, 1, v7
	v_cmp_ne_u32_e32 vcc, v5, v4
	s_and_saveexec_b64 s[8:9], vcc
	s_xor_b64 s[8:9], exec, s[8:9]
	s_cbranch_execz .LBB0_142
	s_waitcnt lgkmcnt(0)
	v_mov_b32_e32 v2, 0x2000
	global_load_dword v2, v2, s[6:7] offset:1024 sc1
	s_add_u32 s14, s6, 0x2400
	s_addc_u32 s15, s7, 0
	s_waitcnt vmcnt(0)
	v_cmp_eq_u32_e32 vcc, v2, v3
	s_and_saveexec_b64 s[10:11], vcc
	s_cbranch_execz .LBB0_141
	s_add_u32 s12, s26, 0x700200
	s_addc_u32 s13, s27, 0
	s_mov_b32 s23, 1
	s_mov_b64 s[16:17], 0
	v_mov_b32_e32 v2, 0
	s_branch .LBB0_132

; __device__ __forceinline__ unsigned xb_ld(unsigned* p)              { return __hip_atomic_load(p, __ATOMIC_RELAXED, __HIP_MEMORY_SCOPE_AGENT); }
; __device__ __forceinline__ unsigned xb_add(unsigned* p, unsigned v) { return __hip_atomic_fetch_add(p, v, __ATOMIC_RELAXED, __HIP_MEMORY_SCOPE_AGENT); }
; #define XB_SPIN(cond, bar) do { unsigned _sp = 0; while (cond) { __builtin_amdgcn_s_sleep(1); \
;     if ((++_sp & 255u) == 0u) { if (xb_ld(&(bar)[XB_TMO])) break; if (_sp > XB_SPIN_CAP) { atomicAdd(&(bar)[XB_TMO], 1u); break; } } } } while (0)
; __device__ __forceinline__ void xcd_barrier(const XcdBarrier& b) {
;     ...
;             __builtin_amdgcn_fence(__ATOMIC_RELEASE, "agent");
;             asm volatile("s_waitcnt vmcnt(0)" ::: "memory");
;             const unsigned og = xb_add(&bar[XB_TOP], 1u);
;             const unsigned tg = og / nx;
;             if (og + 1u == (tg + 1u) * nx) xb_add(&bar[XB_TOPGEN], 1u);
;             else XB_SPIN(xb_ld(&bar[XB_TOPGEN]) == tg, bar);
.LBB0_145:
	s_or_b64 exec, exec, s[10:11]
	s_waitcnt vmcnt(0)
	v_readfirstlane_b32 s8, v4
	v_mul_u32_u24_e32 v2, 2, v2
	s_add_u32 s10, s26, 0x703500
	s_addc_u32 s11, s27, 0
	s_mov_b64 s[12:13], -1
	s_nop 1
	v_add_u32_e32 v3, s8, v3
	v_mov_b32_e32 v4, 1
	v_add_u32_e32 v6, 1, v3
	v_cmp_ne_u32_e32 vcc, v6, v2
	v_mov_b64_e32 v[2:3], s[10:11]
	s_and_saveexec_b64 s[8:9], vcc
	s_cbranch_execz .LBB0_157
	v_mov_b32_e32 v2, 0
	global_load_dword v3, v2, s[10:11] sc1
	s_mov_b64 s[16:17], 0
	s_waitcnt vmcnt(0)
	v_cmp_eq_u32_e32 vcc, v3, v4
	s_and_saveexec_b64 s[14:15], vcc
	s_cbranch_execz .LBB0_156
	s_add_u32 s12, s26, 0x700200
	s_addc_u32 s13, s27, 0
	s_mov_b32 s23, 1
	s_branch .LBB0_149

; __device__ __forceinline__ unsigned xb_ld(unsigned* p)              { return __hip_atomic_load(p, __ATOMIC_RELAXED, __HIP_MEMORY_SCOPE_AGENT); }
; __device__ __forceinline__ unsigned xb_add(unsigned* p, unsigned v) { return __hip_atomic_fetch_add(p, v, __ATOMIC_RELAXED, __HIP_MEMORY_SCOPE_AGENT); }
; #define XB_SPIN(cond, bar) do { unsigned _sp = 0; while (cond) { __builtin_amdgcn_s_sleep(1); \
;     if ((++_sp & 255u) == 0u) { if (xb_ld(&(bar)[XB_TMO])) break; if (_sp > XB_SPIN_CAP) { atomicAdd(&(bar)[XB_TMO], 1u); break; } } } } while (0)
; __device__ __forceinline__ void xcd_barrier(const XcdBarrier& b) {
;     ...
;         const unsigned old = xb_add(&bar[XB_XSUB(b.x)], 1u);
;         const unsigned gen = old / nloc;
;         if (old + 1u == (gen + 1u) * nloc) {
;     ...
;         } else {
;             XB_SPIN(xb_ld(&bar[XB_XGEN(b.x)]) == gen, bar);
.LBB0_457:
	s_or_b64 exec, exec, s[10:11]
	s_waitcnt vmcnt(0)
	v_readfirstlane_b32 s8, v5
	v_mul_u32_u24_e32 v4, 3, v4
	s_nop 1
	v_add_u32_e32 v7, s8, v3
	v_mov_b32_e32 v3, 2
	v_add_u32_e32 v5, 1, v7
	v_cmp_ne_u32_e32 vcc, v5, v4
	s_and_saveexec_b64 s[8:9], vcc
	s_xor_b64 s[8:9], exec, s[8:9]
	s_cbranch_execz .LBB0_471
	s_waitcnt lgkmcnt(0)
	v_mov_b32_e32 v2, 0x2000
	global_load_dword v2, v2, s[6:7] offset:1024 sc1
	s_add_u32 s14, s6, 0x2400
	s_addc_u32 s15, s7, 0
	s_waitcnt vmcnt(0)
	v_cmp_eq_u32_e32 vcc, v2, v3
	s_and_saveexec_b64 s[10:11], vcc
	s_cbranch_execz .LBB0_470
	s_add_u32 s12, s26, 0x700200
	s_addc_u32 s13, s27, 0
	s_mov_b32 s23, 1
	s_mov_b64 s[16:17], 0
	v_mov_b32_e32 v2, 0
	s_branch .LBB0_461

; __device__ __forceinline__ unsigned xb_ld(unsigned* p)              { return __hip_atomic_load(p, __ATOMIC_RELAXED, __HIP_MEMORY_SCOPE_AGENT); }
; __device__ __forceinline__ unsigned xb_add(unsigned* p, unsigned v) { return __hip_atomic_fetch_add(p, v, __ATOMIC_RELAXED, __HIP_MEMORY_SCOPE_AGENT); }
; #define XB_SPIN(cond, bar) do { unsigned _sp = 0; while (cond) { __builtin_amdgcn_s_sleep(1); \
;     if ((++_sp & 255u) == 0u) { if (xb_ld(&(bar)[XB_TMO])) break; if (_sp > XB_SPIN_CAP) { atomicAdd(&(bar)[XB_TMO], 1u); break; } } } } while (0)
; __device__ __forceinline__ void xcd_barrier(const XcdBarrier& b) {
;     ...
;             __builtin_amdgcn_fence(__ATOMIC_RELEASE, "agent");
;             asm volatile("s_waitcnt vmcnt(0)" ::: "memory");
;             const unsigned og = xb_add(&bar[XB_TOP], 1u);
;             const unsigned tg = og / nx;
;             if (og + 1u == (tg + 1u) * nx) xb_add(&bar[XB_TOPGEN], 1u);
;             else XB_SPIN(xb_ld(&bar[XB_TOPGEN]) == tg, bar);
.LBB0_474:
	s_or_b64 exec, exec, s[10:11]
	s_waitcnt vmcnt(0)
	v_readfirstlane_b32 s8, v4
	v_mul_u32_u24_e32 v2, 3, v2
	s_add_u32 s10, s26, 0x703500
	s_addc_u32 s11, s27, 0
	s_mov_b64 s[12:13], -1
	s_nop 1
	v_add_u32_e32 v3, s8, v3
	v_mov_b32_e32 v4, 2
	v_add_u32_e32 v6, 1, v3
	v_cmp_ne_u32_e32 vcc, v6, v2
	v_mov_b64_e32 v[2:3], s[10:11]
	s_and_saveexec_b64 s[8:9], vcc
	s_cbranch_execz .LBB0_486
	v_mov_b32_e32 v2, 0
	global_load_dword v3, v2, s[10:11] sc1
	s_mov_b64 s[16:17], 0
	s_waitcnt vmcnt(0)
	v_cmp_eq_u32_e32 vcc, v3, v4
	s_and_saveexec_b64 s[14:15], vcc
	s_cbranch_execz .LBB0_485
	s_add_u32 s12, s26, 0x700200
	s_addc_u32 s13, s27, 0
	s_mov_b32 s23, 1
	s_branch .LBB0_478

; __device__ __forceinline__ unsigned xb_ld(unsigned* p)              { return __hip_atomic_load(p, __ATOMIC_RELAXED, __HIP_MEMORY_SCOPE_AGENT); }
; __device__ __forceinline__ unsigned xb_add(unsigned* p, unsigned v) { return __hip_atomic_fetch_add(p, v, __ATOMIC_RELAXED, __HIP_MEMORY_SCOPE_AGENT); }
; #define XB_SPIN(cond, bar) do { unsigned _sp = 0; while (cond) { __builtin_amdgcn_s_sleep(1); \
;     if ((++_sp & 255u) == 0u) { if (xb_ld(&(bar)[XB_TMO])) break; if (_sp > XB_SPIN_CAP) { atomicAdd(&(bar)[XB_TMO], 1u); break; } } } } while (0)
; __device__ __forceinline__ void xcd_barrier(const XcdBarrier& b) {
;     ...
;         const unsigned old = xb_add(&bar[XB_XSUB(b.x)], 1u);
;         const unsigned gen = old / nloc;
;         if (old + 1u == (gen + 1u) * nloc) {
;     ...
;         } else {
;             XB_SPIN(xb_ld(&bar[XB_XGEN(b.x)]) == gen, bar);
.LBB0_530:
	s_or_b64 exec, exec, s[10:11]
	s_waitcnt vmcnt(0)
	v_readfirstlane_b32 s8, v5
	v_mul_u32_u24_e32 v4, 4, v4
	s_nop 1
	v_add_u32_e32 v7, s8, v3
	v_mov_b32_e32 v3, 3
	v_add_u32_e32 v5, 1, v7
	v_cmp_ne_u32_e32 vcc, v5, v4
	s_and_saveexec_b64 s[8:9], vcc
	s_xor_b64 s[8:9], exec, s[8:9]
	s_cbranch_execz .LBB0_544
	s_waitcnt lgkmcnt(0)
	v_mov_b32_e32 v2, 0x2000
	global_load_dword v2, v2, s[6:7] offset:1024 sc1
	s_add_u32 s14, s6, 0x2400
	s_addc_u32 s15, s7, 0
	s_waitcnt vmcnt(0)
	v_cmp_eq_u32_e32 vcc, v2, v3
	s_and_saveexec_b64 s[10:11], vcc
	s_cbranch_execz .LBB0_543
	s_add_u32 s12, s26, 0x700200
	s_addc_u32 s13, s27, 0
	s_mov_b32 s23, 1
	s_mov_b64 s[16:17], 0
	v_mov_b32_e32 v2, 0
	s_branch .LBB0_534

; __device__ __forceinline__ unsigned xb_ld(unsigned* p)              { return __hip_atomic_load(p, __ATOMIC_RELAXED, __HIP_MEMORY_SCOPE_AGENT); }
; __device__ __forceinline__ unsigned xb_add(unsigned* p, unsigned v) { return __hip_atomic_fetch_add(p, v, __ATOMIC_RELAXED, __HIP_MEMORY_SCOPE_AGENT); }
; #define XB_SPIN(cond, bar) do { unsigned _sp = 0; while (cond) { __builtin_amdgcn_s_sleep(1); \
;     if ((++_sp & 255u) == 0u) { if (xb_ld(&(bar)[XB_TMO])) break; if (_sp > XB_SPIN_CAP) { atomicAdd(&(bar)[XB_TMO], 1u); break; } } } } while (0)
; __device__ __forceinline__ void xcd_barrier(const XcdBarrier& b) {
;     ...
;             __builtin_amdgcn_fence(__ATOMIC_RELEASE, "agent");
;             asm volatile("s_waitcnt vmcnt(0)" ::: "memory");
;             const unsigned og = xb_add(&bar[XB_TOP], 1u);
;             const unsigned tg = og / nx;
;             if (og + 1u == (tg + 1u) * nx) xb_add(&bar[XB_TOPGEN], 1u);
;             else XB_SPIN(xb_ld(&bar[XB_TOPGEN]) == tg, bar);
.LBB0_547:
	s_or_b64 exec, exec, s[10:11]
	s_waitcnt vmcnt(0)
	v_readfirstlane_b32 s8, v4
	v_mul_u32_u24_e32 v2, 4, v2
	s_add_u32 s10, s26, 0x703500
	s_addc_u32 s11, s27, 0
	s_mov_b64 s[12:13], -1
	s_nop 1
	v_add_u32_e32 v3, s8, v3
	v_mov_b32_e32 v4, 3
	v_add_u32_e32 v6, 1, v3
	v_cmp_ne_u32_e32 vcc, v6, v2
	v_mov_b64_e32 v[2:3], s[10:11]
	s_and_saveexec_b64 s[8:9], vcc
	s_cbranch_execz .LBB0_559
	v_mov_b32_e32 v2, 0
	global_load_dword v3, v2, s[10:11] sc1
	s_mov_b64 s[16:17], 0
	s_waitcnt vmcnt(0)
	v_cmp_eq_u32_e32 vcc, v3, v4
	s_and_saveexec_b64 s[14:15], vcc
	s_cbranch_execz .LBB0_558
	s_add_u32 s12, s26, 0x700200
	s_addc_u32 s13, s27, 0
	s_mov_b32 s23, 1
	s_branch .LBB0_551

; __device__ __forceinline__ unsigned xb_ld(unsigned* p)              { return __hip_atomic_load(p, __ATOMIC_RELAXED, __HIP_MEMORY_SCOPE_AGENT); }
; __device__ __forceinline__ unsigned xb_add(unsigned* p, unsigned v) { return __hip_atomic_fetch_add(p, v, __ATOMIC_RELAXED, __HIP_MEMORY_SCOPE_AGENT); }
; #define XB_SPIN(cond, bar) do { unsigned _sp = 0; while (cond) { __builtin_amdgcn_s_sleep(1); \
;     if ((++_sp & 255u) == 0u) { if (xb_ld(&(bar)[XB_TMO])) break; if (_sp > XB_SPIN_CAP) { atomicAdd(&(bar)[XB_TMO], 1u); break; } } } } while (0)
; __device__ __forceinline__ void xcd_barrier(const XcdBarrier& b) {
;     ...
;         const unsigned old = xb_add(&bar[XB_XSUB(b.x)], 1u);
;         const unsigned gen = old / nloc;
;         if (old + 1u == (gen + 1u) * nloc) {
;     ...
;         } else {
;             XB_SPIN(xb_ld(&bar[XB_XGEN(b.x)]) == gen, bar);
.LBB0_676:
	s_or_b64 exec, exec, s[12:13]
	s_waitcnt vmcnt(0)
	v_readfirstlane_b32 s4, v5
	v_mul_u32_u24_e32 v4, 5, v4
	s_nop 1
	v_add_u32_e32 v7, s4, v3
	v_mov_b32_e32 v3, 4
	v_add_u32_e32 v5, 1, v7
	v_cmp_ne_u32_e32 vcc, v5, v4
	s_and_saveexec_b64 s[4:5], vcc
	s_xor_b64 s[10:11], exec, s[4:5]
	s_cbranch_execz .LBB0_690
	s_waitcnt lgkmcnt(0)
	v_mov_b32_e32 v2, 0x2000
	global_load_dword v2, v2, s[8:9] offset:1024 sc1
	s_add_u32 s16, s8, 0x2400
	s_addc_u32 s17, s9, 0
	s_waitcnt vmcnt(0)
	v_cmp_eq_u32_e32 vcc, v2, v3
	s_and_saveexec_b64 s[12:13], vcc
	s_cbranch_execz .LBB0_689
	s_add_u32 s14, s26, 0x700200
	s_addc_u32 s15, s27, 0
	s_mov_b32 s4, 1
	s_mov_b64 s[18:19], 0
	v_mov_b32_e32 v2, 0
	s_branch .LBB0_680

; __device__ __forceinline__ unsigned xb_ld(unsigned* p)              { return __hip_atomic_load(p, __ATOMIC_RELAXED, __HIP_MEMORY_SCOPE_AGENT); }
; __device__ __forceinline__ unsigned xb_add(unsigned* p, unsigned v) { return __hip_atomic_fetch_add(p, v, __ATOMIC_RELAXED, __HIP_MEMORY_SCOPE_AGENT); }
; #define XB_SPIN(cond, bar) do { unsigned _sp = 0; while (cond) { __builtin_amdgcn_s_sleep(1); \
;     if ((++_sp & 255u) == 0u) { if (xb_ld(&(bar)[XB_TMO])) break; if (_sp > XB_SPIN_CAP) { atomicAdd(&(bar)[XB_TMO], 1u); break; } } } } while (0)
; __device__ __forceinline__ void xcd_barrier(const XcdBarrier& b) {
;     ...
;             __builtin_amdgcn_fence(__ATOMIC_RELEASE, "agent");
;             asm volatile("s_waitcnt vmcnt(0)" ::: "memory");
;             const unsigned og = xb_add(&bar[XB_TOP], 1u);
;             const unsigned tg = og / nx;
;             if (og + 1u == (tg + 1u) * nx) xb_add(&bar[XB_TOPGEN], 1u);
;             else XB_SPIN(xb_ld(&bar[XB_TOPGEN]) == tg, bar);
.LBB0_693:
	s_or_b64 exec, exec, s[12:13]
	s_waitcnt vmcnt(0)
	v_readfirstlane_b32 s4, v4
	v_mul_u32_u24_e32 v2, 5, v2
	s_add_u32 s12, s26, 0x703500
	s_addc_u32 s13, s27, 0
	s_mov_b64 s[14:15], -1
	s_nop 1
	v_add_u32_e32 v3, s4, v3
	v_mov_b32_e32 v4, 4
	v_add_u32_e32 v6, 1, v3
	v_cmp_ne_u32_e32 vcc, v6, v2
	v_mov_b64_e32 v[2:3], s[12:13]
	s_and_saveexec_b64 s[10:11], vcc
	s_cbranch_execz .LBB0_705
	v_mov_b32_e32 v2, 0
	global_load_dword v3, v2, s[12:13] sc1
	s_mov_b64 s[18:19], 0
	s_waitcnt vmcnt(0)
	v_cmp_eq_u32_e32 vcc, v3, v4
	s_and_saveexec_b64 s[16:17], vcc
	s_cbranch_execz .LBB0_704
	s_add_u32 s14, s26, 0x700200
	s_addc_u32 s15, s27, 0
	s_mov_b32 s4, 1
	s_branch .LBB0_697

; __device__ __forceinline__ unsigned xb_ld(unsigned* p)              { return __hip_atomic_load(p, __ATOMIC_RELAXED, __HIP_MEMORY_SCOPE_AGENT); }
; __device__ __forceinline__ unsigned xb_add(unsigned* p, unsigned v) { return __hip_atomic_fetch_add(p, v, __ATOMIC_RELAXED, __HIP_MEMORY_SCOPE_AGENT); }
; #define XB_SPIN(cond, bar) do { unsigned _sp = 0; while (cond) { __builtin_amdgcn_s_sleep(1); \
;     if ((++_sp & 255u) == 0u) { if (xb_ld(&(bar)[XB_TMO])) break; if (_sp > XB_SPIN_CAP) { atomicAdd(&(bar)[XB_TMO], 1u); break; } } } } while (0)
; __device__ __forceinline__ void xcd_barrier(const XcdBarrier& b) {
;     ...
;         const unsigned old = xb_add(&bar[XB_XSUB(b.x)], 1u);
;         const unsigned gen = old / nloc;
;         if (old + 1u == (gen + 1u) * nloc) {
;     ...
;         } else {
;             XB_SPIN(xb_ld(&bar[XB_XGEN(b.x)]) == gen, bar);
.LBB0_791:
	s_or_b64 exec, exec, s[12:13]
	s_waitcnt vmcnt(0)
	v_readfirstlane_b32 s4, v5
	v_mul_u32_u24_e32 v4, 6, v4
	s_nop 1
	v_add_u32_e32 v7, s4, v3
	v_mov_b32_e32 v3, 5
	v_add_u32_e32 v5, 1, v7
	v_cmp_ne_u32_e32 vcc, v5, v4
	s_and_saveexec_b64 s[4:5], vcc
	s_xor_b64 s[10:11], exec, s[4:5]
	s_cbranch_execz .LBB0_805
	s_waitcnt lgkmcnt(0)
	v_mov_b32_e32 v2, 0x2000
	global_load_dword v2, v2, s[8:9] offset:1024 sc1
	s_add_u32 s16, s8, 0x2400
	s_addc_u32 s17, s9, 0
	s_waitcnt vmcnt(0)
	v_cmp_eq_u32_e32 vcc, v2, v3
	s_and_saveexec_b64 s[12:13], vcc
	s_cbranch_execz .LBB0_804
	s_add_u32 s14, s26, 0x700200
	s_addc_u32 s15, s27, 0
	s_mov_b32 s4, 1
	s_mov_b64 s[18:19], 0
	v_mov_b32_e32 v2, 0
	s_branch .LBB0_795

; __device__ __forceinline__ unsigned xb_ld(unsigned* p)              { return __hip_atomic_load(p, __ATOMIC_RELAXED, __HIP_MEMORY_SCOPE_AGENT); }
; __device__ __forceinline__ unsigned xb_add(unsigned* p, unsigned v) { return __hip_atomic_fetch_add(p, v, __ATOMIC_RELAXED, __HIP_MEMORY_SCOPE_AGENT); }
; #define XB_SPIN(cond, bar) do { unsigned _sp = 0; while (cond) { __builtin_amdgcn_s_sleep(1); \
;     if ((++_sp & 255u) == 0u) { if (xb_ld(&(bar)[XB_TMO])) break; if (_sp > XB_SPIN_CAP) { atomicAdd(&(bar)[XB_TMO], 1u); break; } } } } while (0)
; __device__ __forceinline__ void xcd_barrier(const XcdBarrier& b) {
;     ...
;             __builtin_amdgcn_fence(__ATOMIC_RELEASE, "agent");
;             asm volatile("s_waitcnt vmcnt(0)" ::: "memory");
;             const unsigned og = xb_add(&bar[XB_TOP], 1u);
;             const unsigned tg = og / nx;
;             if (og + 1u == (tg + 1u) * nx) xb_add(&bar[XB_TOPGEN], 1u);
;             else XB_SPIN(xb_ld(&bar[XB_TOPGEN]) == tg, bar);
.LBB0_808:
	s_or_b64 exec, exec, s[12:13]
	s_waitcnt vmcnt(0)
	v_readfirstlane_b32 s4, v4
	v_mul_u32_u24_e32 v2, 6, v2
	s_add_u32 s12, s26, 0x703500
	s_addc_u32 s13, s27, 0
	s_mov_b64 s[14:15], -1
	s_nop 1
	v_add_u32_e32 v3, s4, v3
	v_mov_b32_e32 v4, 5
	v_add_u32_e32 v6, 1, v3
	v_cmp_ne_u32_e32 vcc, v6, v2
	v_mov_b64_e32 v[2:3], s[12:13]
	s_and_saveexec_b64 s[10:11], vcc
	s_cbranch_execz .LBB0_820
	v_mov_b32_e32 v2, 0
	global_load_dword v3, v2, s[12:13] sc1
	s_mov_b64 s[18:19], 0
	s_waitcnt vmcnt(0)
	v_cmp_eq_u32_e32 vcc, v3, v4
	s_and_saveexec_b64 s[16:17], vcc
	s_cbranch_execz .LBB0_819
	s_add_u32 s14, s26, 0x700200
	s_addc_u32 s15, s27, 0
	s_mov_b32 s4, 1
	s_branch .LBB0_812

; __device__ __forceinline__ unsigned xb_ld(unsigned* p)              { return __hip_atomic_load(p, __ATOMIC_RELAXED, __HIP_MEMORY_SCOPE_AGENT); }
; __device__ __forceinline__ unsigned xb_add(unsigned* p, unsigned v) { return __hip_atomic_fetch_add(p, v, __ATOMIC_RELAXED, __HIP_MEMORY_SCOPE_AGENT); }
; #define XB_SPIN(cond, bar) do { unsigned _sp = 0; while (cond) { __builtin_amdgcn_s_sleep(1); \
;     if ((++_sp & 255u) == 0u) { if (xb_ld(&(bar)[XB_TMO])) break; if (_sp > XB_SPIN_CAP) { atomicAdd(&(bar)[XB_TMO], 1u); break; } } } } while (0)
; __device__ __forceinline__ void xcd_barrier(const XcdBarrier& b) {
;     ...
;         const unsigned old = xb_add(&bar[XB_XSUB(b.x)], 1u);
;         const unsigned gen = old / nloc;
;         if (old + 1u == (gen + 1u) * nloc) {
;     ...
;         } else {
;             XB_SPIN(xb_ld(&bar[XB_XGEN(b.x)]) == gen, bar);
.LBB0_868:
	s_or_b64 exec, exec, s[12:13]
	s_waitcnt vmcnt(0)
	v_readfirstlane_b32 s4, v5
	v_mul_u32_u24_e32 v4, 7, v4
	s_nop 1
	v_add_u32_e32 v7, s4, v3
	v_mov_b32_e32 v3, 6
	v_add_u32_e32 v5, 1, v7
	v_cmp_ne_u32_e32 vcc, v5, v4
	s_and_saveexec_b64 s[4:5], vcc
	s_xor_b64 s[10:11], exec, s[4:5]
	s_cbranch_execz .LBB0_882
	s_waitcnt lgkmcnt(0)
	v_mov_b32_e32 v2, 0x2000
	global_load_dword v2, v2, s[8:9] offset:1024 sc1
	s_add_u32 s16, s8, 0x2400
	s_addc_u32 s17, s9, 0
	s_waitcnt vmcnt(0)
	v_cmp_eq_u32_e32 vcc, v2, v3
	s_and_saveexec_b64 s[12:13], vcc
	s_cbranch_execz .LBB0_881
	s_add_u32 s14, s26, 0x700200
	s_addc_u32 s15, s27, 0
	s_mov_b32 s4, 1
	s_mov_b64 s[18:19], 0
	v_mov_b32_e32 v2, 0
	s_branch .LBB0_872

; __device__ __forceinline__ unsigned xb_ld(unsigned* p)              { return __hip_atomic_load(p, __ATOMIC_RELAXED, __HIP_MEMORY_SCOPE_AGENT); }
; __device__ __forceinline__ unsigned xb_add(unsigned* p, unsigned v) { return __hip_atomic_fetch_add(p, v, __ATOMIC_RELAXED, __HIP_MEMORY_SCOPE_AGENT); }
; #define XB_SPIN(cond, bar) do { unsigned _sp = 0; while (cond) { __builtin_amdgcn_s_sleep(1); \
;     if ((++_sp & 255u) == 0u) { if (xb_ld(&(bar)[XB_TMO])) break; if (_sp > XB_SPIN_CAP) { atomicAdd(&(bar)[XB_TMO], 1u); break; } } } } while (0)
; __device__ __forceinline__ void xcd_barrier(const XcdBarrier& b) {
;     ...
;             __builtin_amdgcn_fence(__ATOMIC_RELEASE, "agent");
;             asm volatile("s_waitcnt vmcnt(0)" ::: "memory");
;             const unsigned og = xb_add(&bar[XB_TOP], 1u);
;             const unsigned tg = og / nx;
;             if (og + 1u == (tg + 1u) * nx) xb_add(&bar[XB_TOPGEN], 1u);
;             else XB_SPIN(xb_ld(&bar[XB_TOPGEN]) == tg, bar);
.LBB0_885:
	s_or_b64 exec, exec, s[12:13]
	s_waitcnt vmcnt(0)
	v_readfirstlane_b32 s4, v4
	v_mul_u32_u24_e32 v2, 7, v2
	s_add_u32 s12, s26, 0x703500
	s_addc_u32 s13, s27, 0
	s_mov_b64 s[14:15], -1
	s_nop 1
	v_add_u32_e32 v3, s4, v3
	v_mov_b32_e32 v4, 6
	v_add_u32_e32 v6, 1, v3
	v_cmp_ne_u32_e32 vcc, v6, v2
	v_mov_b64_e32 v[2:3], s[12:13]
	s_and_saveexec_b64 s[10:11], vcc
	s_cbranch_execz .LBB0_897
	v_mov_b32_e32 v2, 0
	global_load_dword v3, v2, s[12:13] sc1
	s_mov_b64 s[18:19], 0
	s_waitcnt vmcnt(0)
	v_cmp_eq_u32_e32 vcc, v3, v4
	s_and_saveexec_b64 s[16:17], vcc
	s_cbranch_execz .LBB0_896
	s_add_u32 s14, s26, 0x700200
	s_addc_u32 s15, s27, 0
	s_mov_b32 s4, 1
	s_branch .LBB0_889

; __device__ __forceinline__ unsigned xb_ld(unsigned* p)              { return __hip_atomic_load(p, __ATOMIC_RELAXED, __HIP_MEMORY_SCOPE_AGENT); }
; __device__ __forceinline__ unsigned xb_add(unsigned* p, unsigned v) { return __hip_atomic_fetch_add(p, v, __ATOMIC_RELAXED, __HIP_MEMORY_SCOPE_AGENT); }
; #define XB_SPIN(cond, bar) do { unsigned _sp = 0; while (cond) { __builtin_amdgcn_s_sleep(1); \
;     if ((++_sp & 255u) == 0u) { if (xb_ld(&(bar)[XB_TMO])) break; if (_sp > XB_SPIN_CAP) { atomicAdd(&(bar)[XB_TMO], 1u); break; } } } } while (0)
; __device__ __forceinline__ void xcd_barrier(const XcdBarrier& b) {
;     ...
;         const unsigned old = xb_add(&bar[XB_XSUB(b.x)], 1u);
;         const unsigned gen = old / nloc;
;         if (old + 1u == (gen + 1u) * nloc) {
;     ...
;         } else {
;             XB_SPIN(xb_ld(&bar[XB_XGEN(b.x)]) == gen, bar);
.LBB0_1031:
	s_or_b64 exec, exec, s[12:13]
	s_waitcnt vmcnt(0)
	v_readfirstlane_b32 s4, v5
	v_mul_u32_u24_e32 v4, 8, v4
	s_nop 1
	v_add_u32_e32 v7, s4, v3
	v_mov_b32_e32 v3, 7
	v_add_u32_e32 v5, 1, v7
	v_cmp_ne_u32_e32 vcc, v5, v4
	s_and_saveexec_b64 s[4:5], vcc
	s_xor_b64 s[10:11], exec, s[4:5]
	s_cbranch_execz .LBB0_1045
	s_waitcnt lgkmcnt(0)
	v_mov_b32_e32 v2, 0x2000
	global_load_dword v2, v2, s[8:9] offset:1024 sc1
	s_add_u32 s16, s8, 0x2400
	s_addc_u32 s17, s9, 0
	s_waitcnt vmcnt(0)
	v_cmp_eq_u32_e32 vcc, v2, v3
	s_and_saveexec_b64 s[12:13], vcc
	s_cbranch_execz .LBB0_1044
	s_add_u32 s14, s26, 0x700200
	s_addc_u32 s15, s27, 0
	s_mov_b32 s4, 1
	s_mov_b64 s[18:19], 0
	v_mov_b32_e32 v2, 0
	s_branch .LBB0_1035

; __device__ __forceinline__ unsigned xb_ld(unsigned* p)              { return __hip_atomic_load(p, __ATOMIC_RELAXED, __HIP_MEMORY_SCOPE_AGENT); }
; __device__ __forceinline__ unsigned xb_add(unsigned* p, unsigned v) { return __hip_atomic_fetch_add(p, v, __ATOMIC_RELAXED, __HIP_MEMORY_SCOPE_AGENT); }
; #define XB_SPIN(cond, bar) do { unsigned _sp = 0; while (cond) { __builtin_amdgcn_s_sleep(1); \
;     if ((++_sp & 255u) == 0u) { if (xb_ld(&(bar)[XB_TMO])) break; if (_sp > XB_SPIN_CAP) { atomicAdd(&(bar)[XB_TMO], 1u); break; } } } } while (0)
; __device__ __forceinline__ void xcd_barrier(const XcdBarrier& b) {
;     ...
;             __builtin_amdgcn_fence(__ATOMIC_RELEASE, "agent");
;             asm volatile("s_waitcnt vmcnt(0)" ::: "memory");
;             const unsigned og = xb_add(&bar[XB_TOP], 1u);
;             const unsigned tg = og / nx;
;             if (og + 1u == (tg + 1u) * nx) xb_add(&bar[XB_TOPGEN], 1u);
;             else XB_SPIN(xb_ld(&bar[XB_TOPGEN]) == tg, bar);
.LBB0_1048:
	s_or_b64 exec, exec, s[12:13]
	s_waitcnt vmcnt(0)
	v_readfirstlane_b32 s4, v4
	v_mul_u32_u24_e32 v2, 8, v2
	s_add_u32 s12, s26, 0x703500
	s_addc_u32 s13, s27, 0
	s_mov_b64 s[14:15], -1
	s_nop 1
	v_add_u32_e32 v3, s4, v3
	v_mov_b32_e32 v4, 7
	v_add_u32_e32 v6, 1, v3
	v_cmp_ne_u32_e32 vcc, v6, v2
	v_mov_b64_e32 v[2:3], s[12:13]
	s_and_saveexec_b64 s[10:11], vcc
	s_cbranch_execz .LBB0_1060
	v_mov_b32_e32 v2, 0
	global_load_dword v3, v2, s[12:13] sc1
	s_mov_b64 s[18:19], 0
	s_waitcnt vmcnt(0)
	v_cmp_eq_u32_e32 vcc, v3, v4
	s_and_saveexec_b64 s[16:17], vcc
	s_cbranch_execz .LBB0_1059
	s_add_u32 s14, s26, 0x700200
	s_addc_u32 s15, s27, 0
	s_mov_b32 s4, 1
	s_branch .LBB0_1052

; __device__ __forceinline__ unsigned xb_ld(unsigned* p)              { return __hip_atomic_load(p, __ATOMIC_RELAXED, __HIP_MEMORY_SCOPE_AGENT); }
; __device__ __forceinline__ unsigned xb_add(unsigned* p, unsigned v) { return __hip_atomic_fetch_add(p, v, __ATOMIC_RELAXED, __HIP_MEMORY_SCOPE_AGENT); }
; #define XB_SPIN(cond, bar) do { unsigned _sp = 0; while (cond) { __builtin_amdgcn_s_sleep(1); \
;     if ((++_sp & 255u) == 0u) { if (xb_ld(&(bar)[XB_TMO])) break; if (_sp > XB_SPIN_CAP) { atomicAdd(&(bar)[XB_TMO], 1u); break; } } } } while (0)
; __device__ __forceinline__ void xcd_barrier(const XcdBarrier& b) {
;     ...
;         const unsigned old = xb_add(&bar[XB_XSUB(b.x)], 1u);
;         const unsigned gen = old / nloc;
;         if (old + 1u == (gen + 1u) * nloc) {
;     ...
;         } else {
;             XB_SPIN(xb_ld(&bar[XB_XGEN(b.x)]) == gen, bar);
.LBB0_1360:
	s_or_b64 exec, exec, s[12:13]
	s_waitcnt vmcnt(0)
	v_readfirstlane_b32 s4, v5
	v_mul_u32_u24_e32 v4, 9, v4
	s_nop 1
	v_add_u32_e32 v7, s4, v3
	v_mov_b32_e32 v3, 8
	v_add_u32_e32 v5, 1, v7
	v_cmp_ne_u32_e32 vcc, v5, v4
	s_and_saveexec_b64 s[4:5], vcc
	s_xor_b64 s[10:11], exec, s[4:5]
	s_cbranch_execz .LBB0_1374
	s_waitcnt lgkmcnt(0)
	v_mov_b32_e32 v2, 0x2000
	global_load_dword v2, v2, s[8:9] offset:1024 sc1
	s_add_u32 s16, s8, 0x2400
	s_addc_u32 s17, s9, 0
	s_waitcnt vmcnt(0)
	v_cmp_eq_u32_e32 vcc, v2, v3
	s_and_saveexec_b64 s[12:13], vcc
	s_cbranch_execz .LBB0_1373
	s_add_u32 s14, s26, 0x700200
	s_addc_u32 s15, s27, 0
	s_mov_b32 s4, 1
	s_mov_b64 s[18:19], 0
	v_mov_b32_e32 v2, 0
	s_branch .LBB0_1364

; __device__ __forceinline__ unsigned xb_ld(unsigned* p)              { return __hip_atomic_load(p, __ATOMIC_RELAXED, __HIP_MEMORY_SCOPE_AGENT); }
; __device__ __forceinline__ unsigned xb_add(unsigned* p, unsigned v) { return __hip_atomic_fetch_add(p, v, __ATOMIC_RELAXED, __HIP_MEMORY_SCOPE_AGENT); }
; #define XB_SPIN(cond, bar) do { unsigned _sp = 0; while (cond) { __builtin_amdgcn_s_sleep(1); \
;     if ((++_sp & 255u) == 0u) { if (xb_ld(&(bar)[XB_TMO])) break; if (_sp > XB_SPIN_CAP) { atomicAdd(&(bar)[XB_TMO], 1u); break; } } } } while (0)
; __device__ __forceinline__ void xcd_barrier(const XcdBarrier& b) {
;     ...
;             __builtin_amdgcn_fence(__ATOMIC_RELEASE, "agent");
;             asm volatile("s_waitcnt vmcnt(0)" ::: "memory");
;             const unsigned og = xb_add(&bar[XB_TOP], 1u);
;             const unsigned tg = og / nx;
;             if (og + 1u == (tg + 1u) * nx) xb_add(&bar[XB_TOPGEN], 1u);
;             else XB_SPIN(xb_ld(&bar[XB_TOPGEN]) == tg, bar);
.LBB0_1377:
	s_or_b64 exec, exec, s[12:13]
	s_waitcnt vmcnt(0)
	v_readfirstlane_b32 s4, v4
	v_mul_u32_u24_e32 v2, 9, v2
	s_add_u32 s12, s26, 0x703500
	s_addc_u32 s13, s27, 0
	s_mov_b64 s[14:15], -1
	s_nop 1
	v_add_u32_e32 v3, s4, v3
	v_mov_b32_e32 v4, 8
	v_add_u32_e32 v6, 1, v3
	v_cmp_ne_u32_e32 vcc, v6, v2
	v_mov_b64_e32 v[2:3], s[12:13]
	s_and_saveexec_b64 s[10:11], vcc
	s_cbranch_execz .LBB0_1389
	v_mov_b32_e32 v2, 0
	global_load_dword v3, v2, s[12:13] sc1
	s_mov_b64 s[18:19], 0
	s_waitcnt vmcnt(0)
	v_cmp_eq_u32_e32 vcc, v3, v4
	s_and_saveexec_b64 s[16:17], vcc
	s_cbranch_execz .LBB0_1388
	s_add_u32 s14, s26, 0x700200
	s_addc_u32 s15, s27, 0
	s_mov_b32 s4, 1
	s_branch .LBB0_1381

; __device__ __forceinline__ unsigned xb_ld(unsigned* p)              { return __hip_atomic_load(p, __ATOMIC_RELAXED, __HIP_MEMORY_SCOPE_AGENT); }
; __device__ __forceinline__ unsigned xb_add(unsigned* p, unsigned v) { return __hip_atomic_fetch_add(p, v, __ATOMIC_RELAXED, __HIP_MEMORY_SCOPE_AGENT); }
; #define XB_SPIN(cond, bar) do { unsigned _sp = 0; while (cond) { __builtin_amdgcn_s_sleep(1); \
;     if ((++_sp & 255u) == 0u) { if (xb_ld(&(bar)[XB_TMO])) break; if (_sp > XB_SPIN_CAP) { atomicAdd(&(bar)[XB_TMO], 1u); break; } } } } while (0)
; __device__ __forceinline__ void xcd_barrier(const XcdBarrier& b) {
;     ...
;         const unsigned old = xb_add(&bar[XB_XSUB(b.x)], 1u);
;         const unsigned gen = old / nloc;
;         if (old + 1u == (gen + 1u) * nloc) {
;     ...
;         } else {
;             XB_SPIN(xb_ld(&bar[XB_XGEN(b.x)]) == gen, bar);
.LBB0_1433:
	s_or_b64 exec, exec, s[12:13]
	s_waitcnt vmcnt(0)
	v_readfirstlane_b32 s4, v5
	v_mul_u32_u24_e32 v4, 10, v4
	s_nop 1
	v_add_u32_e32 v7, s4, v3
	v_mov_b32_e32 v3, 9
	v_add_u32_e32 v5, 1, v7
	v_cmp_ne_u32_e32 vcc, v5, v4
	s_and_saveexec_b64 s[4:5], vcc
	s_xor_b64 s[10:11], exec, s[4:5]
	s_cbranch_execz .LBB0_1447
	s_waitcnt lgkmcnt(0)
	v_mov_b32_e32 v2, 0x2000
	global_load_dword v2, v2, s[8:9] offset:1024 sc1
	s_add_u32 s16, s8, 0x2400
	s_addc_u32 s17, s9, 0
	s_waitcnt vmcnt(0)
	v_cmp_eq_u32_e32 vcc, v2, v3
	s_and_saveexec_b64 s[12:13], vcc
	s_cbranch_execz .LBB0_1446
	s_add_u32 s14, s26, 0x700200
	s_addc_u32 s15, s27, 0
	s_mov_b32 s4, 1
	s_mov_b64 s[18:19], 0
	v_mov_b32_e32 v2, 0
	s_branch .LBB0_1437

; __device__ __forceinline__ unsigned xb_ld(unsigned* p)              { return __hip_atomic_load(p, __ATOMIC_RELAXED, __HIP_MEMORY_SCOPE_AGENT); }
; __device__ __forceinline__ unsigned xb_add(unsigned* p, unsigned v) { return __hip_atomic_fetch_add(p, v, __ATOMIC_RELAXED, __HIP_MEMORY_SCOPE_AGENT); }
; #define XB_SPIN(cond, bar) do { unsigned _sp = 0; while (cond) { __builtin_amdgcn_s_sleep(1); \
;     if ((++_sp & 255u) == 0u) { if (xb_ld(&(bar)[XB_TMO])) break; if (_sp > XB_SPIN_CAP) { atomicAdd(&(bar)[XB_TMO], 1u); break; } } } } while (0)
; __device__ __forceinline__ void xcd_barrier(const XcdBarrier& b) {
;     ...
;             __builtin_amdgcn_fence(__ATOMIC_RELEASE, "agent");
;             asm volatile("s_waitcnt vmcnt(0)" ::: "memory");
;             const unsigned og = xb_add(&bar[XB_TOP], 1u);
;             const unsigned tg = og / nx;
;             if (og + 1u == (tg + 1u) * nx) xb_add(&bar[XB_TOPGEN], 1u);
;             else XB_SPIN(xb_ld(&bar[XB_TOPGEN]) == tg, bar);
.LBB0_1450:
	s_or_b64 exec, exec, s[12:13]
	s_waitcnt vmcnt(0)
	v_readfirstlane_b32 s4, v4
	v_mul_u32_u24_e32 v2, 10, v2
	s_add_u32 s12, s26, 0x703500
	s_addc_u32 s13, s27, 0
	s_mov_b64 s[14:15], -1
	s_nop 1
	v_add_u32_e32 v3, s4, v3
	v_mov_b32_e32 v4, 9
	v_add_u32_e32 v6, 1, v3
	v_cmp_ne_u32_e32 vcc, v6, v2
	v_mov_b64_e32 v[2:3], s[12:13]
	s_and_saveexec_b64 s[10:11], vcc
	s_cbranch_execz .LBB0_1462
	v_mov_b32_e32 v2, 0
	global_load_dword v3, v2, s[12:13] sc1
	s_mov_b64 s[18:19], 0
	s_waitcnt vmcnt(0)
	v_cmp_eq_u32_e32 vcc, v3, v4
	s_and_saveexec_b64 s[16:17], vcc
	s_cbranch_execz .LBB0_1461
	s_add_u32 s14, s26, 0x700200
	s_addc_u32 s15, s27, 0
	s_mov_b32 s4, 1
	s_branch .LBB0_1454

; __device__ __forceinline__ unsigned xb_ld(unsigned* p)              { return __hip_atomic_load(p, __ATOMIC_RELAXED, __HIP_MEMORY_SCOPE_AGENT); }
; __device__ __forceinline__ unsigned xb_add(unsigned* p, unsigned v) { return __hip_atomic_fetch_add(p, v, __ATOMIC_RELAXED, __HIP_MEMORY_SCOPE_AGENT); }
; #define XB_SPIN(cond, bar) do { unsigned _sp = 0; while (cond) { __builtin_amdgcn_s_sleep(1); \
;     if ((++_sp & 255u) == 0u) { if (xb_ld(&(bar)[XB_TMO])) break; if (_sp > XB_SPIN_CAP) { atomicAdd(&(bar)[XB_TMO], 1u); break; } } } } while (0)
; __device__ __forceinline__ void xcd_barrier(const XcdBarrier& b) {
;     ...
;         const unsigned old = xb_add(&bar[XB_XSUB(b.x)], 1u);
;         const unsigned gen = old / nloc;
;         if (old + 1u == (gen + 1u) * nloc) {
;     ...
;         } else {
;             XB_SPIN(xb_ld(&bar[XB_XGEN(b.x)]) == gen, bar);
.LBB0_1579:
	s_or_b64 exec, exec, s[12:13]
	s_waitcnt vmcnt(0)
	v_readfirstlane_b32 s4, v5
	v_mul_u32_u24_e32 v4, 11, v4
	s_nop 1
	v_add_u32_e32 v7, s4, v3
	v_mov_b32_e32 v3, 10
	v_add_u32_e32 v5, 1, v7
	v_cmp_ne_u32_e32 vcc, v5, v4
	s_and_saveexec_b64 s[4:5], vcc
	s_xor_b64 s[10:11], exec, s[4:5]
	s_cbranch_execz .LBB0_1593
	s_waitcnt lgkmcnt(0)
	v_mov_b32_e32 v2, 0x2000
	global_load_dword v2, v2, s[8:9] offset:1024 sc1
	s_add_u32 s16, s8, 0x2400
	s_addc_u32 s17, s9, 0
	s_waitcnt vmcnt(0)
	v_cmp_eq_u32_e32 vcc, v2, v3
	s_and_saveexec_b64 s[12:13], vcc
	s_cbranch_execz .LBB0_1592
	s_add_u32 s14, s26, 0x700200
	s_addc_u32 s15, s27, 0
	s_mov_b32 s4, 1
	s_mov_b64 s[18:19], 0
	v_mov_b32_e32 v2, 0
	s_branch .LBB0_1583

; __device__ __forceinline__ unsigned xb_ld(unsigned* p)              { return __hip_atomic_load(p, __ATOMIC_RELAXED, __HIP_MEMORY_SCOPE_AGENT); }
; __device__ __forceinline__ unsigned xb_add(unsigned* p, unsigned v) { return __hip_atomic_fetch_add(p, v, __ATOMIC_RELAXED, __HIP_MEMORY_SCOPE_AGENT); }
; #define XB_SPIN(cond, bar) do { unsigned _sp = 0; while (cond) { __builtin_amdgcn_s_sleep(1); \
;     if ((++_sp & 255u) == 0u) { if (xb_ld(&(bar)[XB_TMO])) break; if (_sp > XB_SPIN_CAP) { atomicAdd(&(bar)[XB_TMO], 1u); break; } } } } while (0)
; __device__ __forceinline__ void xcd_barrier(const XcdBarrier& b) {
;     ...
;             __builtin_amdgcn_fence(__ATOMIC_RELEASE, "agent");
;             asm volatile("s_waitcnt vmcnt(0)" ::: "memory");
;             const unsigned og = xb_add(&bar[XB_TOP], 1u);
;             const unsigned tg = og / nx;
;             if (og + 1u == (tg + 1u) * nx) xb_add(&bar[XB_TOPGEN], 1u);
;             else XB_SPIN(xb_ld(&bar[XB_TOPGEN]) == tg, bar);
.LBB0_1596:
	s_or_b64 exec, exec, s[12:13]
	s_waitcnt vmcnt(0)
	v_readfirstlane_b32 s4, v4
	v_mul_u32_u24_e32 v2, 11, v2
	s_add_u32 s12, s26, 0x703500
	s_addc_u32 s13, s27, 0
	s_mov_b64 s[14:15], -1
	s_nop 1
	v_add_u32_e32 v3, s4, v3
	v_mov_b32_e32 v4, 10
	v_add_u32_e32 v6, 1, v3
	v_cmp_ne_u32_e32 vcc, v6, v2
	v_mov_b64_e32 v[2:3], s[12:13]
	s_and_saveexec_b64 s[10:11], vcc
	s_cbranch_execz .LBB0_1608
	v_mov_b32_e32 v2, 0
	global_load_dword v3, v2, s[12:13] sc1
	s_mov_b64 s[18:19], 0
	s_waitcnt vmcnt(0)
	v_cmp_eq_u32_e32 vcc, v3, v4
	s_and_saveexec_b64 s[16:17], vcc
	s_cbranch_execz .LBB0_1607
	s_add_u32 s14, s26, 0x700200
	s_addc_u32 s15, s27, 0
	s_mov_b32 s4, 1
	s_branch .LBB0_1600

; __device__ __forceinline__ unsigned xb_ld(unsigned* p)              { return __hip_atomic_load(p, __ATOMIC_RELAXED, __HIP_MEMORY_SCOPE_AGENT); }
; __device__ __forceinline__ unsigned xb_add(unsigned* p, unsigned v) { return __hip_atomic_fetch_add(p, v, __ATOMIC_RELAXED, __HIP_MEMORY_SCOPE_AGENT); }
; #define XB_SPIN(cond, bar) do { unsigned _sp = 0; while (cond) { __builtin_amdgcn_s_sleep(1); \
;     if ((++_sp & 255u) == 0u) { if (xb_ld(&(bar)[XB_TMO])) break; if (_sp > XB_SPIN_CAP) { atomicAdd(&(bar)[XB_TMO], 1u); break; } } } } while (0)
; __device__ __forceinline__ void xcd_barrier(const XcdBarrier& b) {
;     ...
;         const unsigned old = xb_add(&bar[XB_XSUB(b.x)], 1u);
;         const unsigned gen = old / nloc;
;         if (old + 1u == (gen + 1u) * nloc) {
;     ...
;         } else {
;             XB_SPIN(xb_ld(&bar[XB_XGEN(b.x)]) == gen, bar);
.LBB0_1694:
	s_or_b64 exec, exec, s[12:13]
	s_waitcnt vmcnt(0)
	v_readfirstlane_b32 s4, v5
	v_mul_u32_u24_e32 v4, 12, v4
	s_nop 1
	v_add_u32_e32 v7, s4, v3
	v_mov_b32_e32 v3, 11
	v_add_u32_e32 v5, 1, v7
	v_cmp_ne_u32_e32 vcc, v5, v4
	s_and_saveexec_b64 s[4:5], vcc
	s_xor_b64 s[10:11], exec, s[4:5]
	s_cbranch_execz .LBB0_1708
	s_waitcnt lgkmcnt(0)
	v_mov_b32_e32 v2, 0x2000
	global_load_dword v2, v2, s[8:9] offset:1024 sc1
	s_add_u32 s16, s8, 0x2400
	s_addc_u32 s17, s9, 0
	s_waitcnt vmcnt(0)
	v_cmp_eq_u32_e32 vcc, v2, v3
	s_and_saveexec_b64 s[12:13], vcc
	s_cbranch_execz .LBB0_1707
	s_add_u32 s14, s26, 0x700200
	s_addc_u32 s15, s27, 0
	s_mov_b32 s4, 1
	s_mov_b64 s[18:19], 0
	v_mov_b32_e32 v2, 0
	s_branch .LBB0_1698

; __device__ __forceinline__ unsigned xb_ld(unsigned* p)              { return __hip_atomic_load(p, __ATOMIC_RELAXED, __HIP_MEMORY_SCOPE_AGENT); }
; __device__ __forceinline__ unsigned xb_add(unsigned* p, unsigned v) { return __hip_atomic_fetch_add(p, v, __ATOMIC_RELAXED, __HIP_MEMORY_SCOPE_AGENT); }
; #define XB_SPIN(cond, bar) do { unsigned _sp = 0; while (cond) { __builtin_amdgcn_s_sleep(1); \
;     if ((++_sp & 255u) == 0u) { if (xb_ld(&(bar)[XB_TMO])) break; if (_sp > XB_SPIN_CAP) { atomicAdd(&(bar)[XB_TMO], 1u); break; } } } } while (0)
; __device__ __forceinline__ void xcd_barrier(const XcdBarrier& b) {
;     ...
;             __builtin_amdgcn_fence(__ATOMIC_RELEASE, "agent");
;             asm volatile("s_waitcnt vmcnt(0)" ::: "memory");
;             const unsigned og = xb_add(&bar[XB_TOP], 1u);
;             const unsigned tg = og / nx;
;             if (og + 1u == (tg + 1u) * nx) xb_add(&bar[XB_TOPGEN], 1u);
;             else XB_SPIN(xb_ld(&bar[XB_TOPGEN]) == tg, bar);
.LBB0_1711:
	s_or_b64 exec, exec, s[12:13]
	s_waitcnt vmcnt(0)
	v_readfirstlane_b32 s4, v4
	v_mul_u32_u24_e32 v2, 12, v2
	s_add_u32 s12, s26, 0x703500
	s_addc_u32 s13, s27, 0
	s_mov_b64 s[14:15], -1
	s_nop 1
	v_add_u32_e32 v3, s4, v3
	v_mov_b32_e32 v4, 11
	v_add_u32_e32 v6, 1, v3
	v_cmp_ne_u32_e32 vcc, v6, v2
	v_mov_b64_e32 v[2:3], s[12:13]
	s_and_saveexec_b64 s[10:11], vcc
	s_cbranch_execz .LBB0_1723
	v_mov_b32_e32 v2, 0
	global_load_dword v3, v2, s[12:13] sc1
	s_mov_b64 s[18:19], 0
	s_waitcnt vmcnt(0)
	v_cmp_eq_u32_e32 vcc, v3, v4
	s_and_saveexec_b64 s[16:17], vcc
	s_cbranch_execz .LBB0_1722
	s_add_u32 s14, s26, 0x700200
	s_addc_u32 s15, s27, 0
	s_mov_b32 s4, 1
	s_branch .LBB0_1715

; __device__ __forceinline__ unsigned xb_ld(unsigned* p)              { return __hip_atomic_load(p, __ATOMIC_RELAXED, __HIP_MEMORY_SCOPE_AGENT); }
; __device__ __forceinline__ unsigned xb_add(unsigned* p, unsigned v) { return __hip_atomic_fetch_add(p, v, __ATOMIC_RELAXED, __HIP_MEMORY_SCOPE_AGENT); }
; #define XB_SPIN(cond, bar) do { unsigned _sp = 0; while (cond) { __builtin_amdgcn_s_sleep(1); \
;     if ((++_sp & 255u) == 0u) { if (xb_ld(&(bar)[XB_TMO])) break; if (_sp > XB_SPIN_CAP) { atomicAdd(&(bar)[XB_TMO], 1u); break; } } } } while (0)
; __device__ __forceinline__ void xcd_barrier(const XcdBarrier& b) {
;     ...
;         const unsigned old = xb_add(&bar[XB_XSUB(b.x)], 1u);
;         const unsigned gen = old / nloc;
;         if (old + 1u == (gen + 1u) * nloc) {
;     ...
;         } else {
;             XB_SPIN(xb_ld(&bar[XB_XGEN(b.x)]) == gen, bar);
.LBB0_1771:
	s_or_b64 exec, exec, s[12:13]
	s_waitcnt vmcnt(0)
	v_readfirstlane_b32 s4, v5
	v_mul_u32_u24_e32 v4, 13, v4
	s_nop 1
	v_add_u32_e32 v7, s4, v3
	v_mov_b32_e32 v3, 12
	v_add_u32_e32 v5, 1, v7
	v_cmp_ne_u32_e32 vcc, v5, v4
	s_and_saveexec_b64 s[4:5], vcc
	s_xor_b64 s[10:11], exec, s[4:5]
	s_cbranch_execz .LBB0_1785
	s_waitcnt lgkmcnt(0)
	v_mov_b32_e32 v2, 0x2000
	global_load_dword v2, v2, s[8:9] offset:1024 sc1
	s_add_u32 s16, s8, 0x2400
	s_addc_u32 s17, s9, 0
	s_waitcnt vmcnt(0)
	v_cmp_eq_u32_e32 vcc, v2, v3
	s_and_saveexec_b64 s[12:13], vcc
	s_cbranch_execz .LBB0_1784
	s_add_u32 s14, s26, 0x700200
	s_addc_u32 s15, s27, 0
	s_mov_b32 s4, 1
	s_mov_b64 s[18:19], 0
	v_mov_b32_e32 v2, 0
	s_branch .LBB0_1775

; __device__ __forceinline__ unsigned xb_ld(unsigned* p)              { return __hip_atomic_load(p, __ATOMIC_RELAXED, __HIP_MEMORY_SCOPE_AGENT); }
; __device__ __forceinline__ unsigned xb_add(unsigned* p, unsigned v) { return __hip_atomic_fetch_add(p, v, __ATOMIC_RELAXED, __HIP_MEMORY_SCOPE_AGENT); }
; #define XB_SPIN(cond, bar) do { unsigned _sp = 0; while (cond) { __builtin_amdgcn_s_sleep(1); \
;     if ((++_sp & 255u) == 0u) { if (xb_ld(&(bar)[XB_TMO])) break; if (_sp > XB_SPIN_CAP) { atomicAdd(&(bar)[XB_TMO], 1u); break; } } } } while (0)
; __device__ __forceinline__ void xcd_barrier(const XcdBarrier& b) {
;     ...
;             __builtin_amdgcn_fence(__ATOMIC_RELEASE, "agent");
;             asm volatile("s_waitcnt vmcnt(0)" ::: "memory");
;             const unsigned og = xb_add(&bar[XB_TOP], 1u);
;             const unsigned tg = og / nx;
;             if (og + 1u == (tg + 1u) * nx) xb_add(&bar[XB_TOPGEN], 1u);
;             else XB_SPIN(xb_ld(&bar[XB_TOPGEN]) == tg, bar);
.LBB0_1788:
	s_or_b64 exec, exec, s[12:13]
	s_waitcnt vmcnt(0)
	v_readfirstlane_b32 s4, v4
	v_mul_u32_u24_e32 v2, 13, v2
	s_add_u32 s12, s26, 0x703500
	s_addc_u32 s13, s27, 0
	s_mov_b64 s[14:15], -1
	s_nop 1
	v_add_u32_e32 v3, s4, v3
	v_mov_b32_e32 v4, 12
	v_add_u32_e32 v6, 1, v3
	v_cmp_ne_u32_e32 vcc, v6, v2
	v_mov_b64_e32 v[2:3], s[12:13]
	s_and_saveexec_b64 s[10:11], vcc
	s_cbranch_execz .LBB0_1800
	v_mov_b32_e32 v2, 0
	global_load_dword v3, v2, s[12:13] sc1
	s_mov_b64 s[18:19], 0
	s_waitcnt vmcnt(0)
	v_cmp_eq_u32_e32 vcc, v3, v4
	s_and_saveexec_b64 s[16:17], vcc
	s_cbranch_execz .LBB0_1799
	s_add_u32 s14, s26, 0x700200
	s_addc_u32 s15, s27, 0
	s_mov_b32 s4, 1
	s_branch .LBB0_1792
